# FFN-down GEMM walks the row tiles in reverse so it first reads the U tiles the FFN-up phase wrote last (still in the memory-side cache)
# speedup vs baseline: 1.0034x; 1.0005x over previous
;     __host__ __device__ bool next(int i, Unit& u) const {
;         const long L = (long)i * G + c; if (L >= nwg) return false;
;         int wgid = (int)L; { const int q = nwg / NXCD, r = nwg % NXCD, xcd = wgid % NXCD, off = wgid / NXCD; wgid = (xcd < r ? xcd * (q + 1) : r * (q + 1) + (xcd - r) * q) + off; }
;         const int nig = WGM * nN, gid = wgid / nig, fm = gid * WGM, gsz = (nM - fm) < WGM ? (nM - fm) : WGM;
;         u.pm = fm + ((wgid % nig) % gsz); u.pn = (wgid % nig) / gsz; return true;
;     }
; template <class Epi, class Sched, bool ALIGN_EPI = false, bool SP2 = false>
; __device__ __forceinline__ void gemm_phase(PG8_LAS unsigned char* lds, const Gemm g, const Sched& S, const Epi& E) {
;     ...
;     Unit cur, nxt; int ui = 0;
;     if (!S.next(0, cur)) return;
;     f32x4 acc[2][2][4][2];
; #pragma unroll
;     for (int a = 0; a < 2; ++a)
; #pragma unroll
;         for (int b = 0; b < 2; ++b)
; #pragma unroll
;             for (int m = 0; m < 4; ++m)
; #pragma unroll
;                 for (int n = 0; n < 2; ++n) acc[a][b][m][n] = (f32x4){0.f, 0.f, 0.f, 0.f};
;     bf16x8 At[4][2], B0[2][2], B1[2][2];
;     const char* cA = (const char*)g.A + (size_t)cur.pm * tstepA; const char* cB = (const char*)g.Bt + (size_t)cur.pn * tstepB;
.LBB0_698:
	s_and_b64 vcc, exec, s[4:5]
	s_cbranch_vccz .LBB0_779
	v_mov_b32_e32 v3, v209
	s_and_b64 vcc, exec, s[36:37]
	v_readfirstlane_b32 s4, v3
	s_cbranch_vccnz .LBB0_701
	v_readlane_b32 s19, v255, 27
	v_readlane_b32 s18, v255, 28
	s_sub_i32 s18, s30, s18
	s_add_i32 s18, s18, -1

;     __host__ __device__ bool next(int i, Unit& u) const {
;         const long L = (long)i * G + c; if (L >= nwg) return false;
;         int wgid = (int)L; { const int q = nwg / NXCD, r = nwg % NXCD, xcd = wgid % NXCD, off = wgid / NXCD; wgid = (xcd < r ? xcd * (q + 1) : r * (q + 1) + (xcd - r) * q) + off; }
;         const int nig = WGM * nN, gid = wgid / nig, fm = gid * WGM, gsz = (nM - fm) < WGM ? (nM - fm) : WGM;
;         u.pm = fm + ((wgid % nig) % gsz); u.pn = (wgid % nig) / gsz; return true;
;     }
; template <class Epi, class Sched, bool ALIGN_EPI = false, bool SP2 = false>
; __device__ __forceinline__ void gemm_phase(PG8_LAS unsigned char* lds, const Gemm g, const Sched& S, const Epi& E) {
;     ...
;         const bool has_next = S.next(ui + 1, nxt);
;         const char* nA = has_next ? (const char*)g.A + (size_t)nxt.pm * tstepA : cA; const char* nB = has_next ? (const char*)g.Bt + (size_t)nxt.pn * tstepB : cB;
.LBB0_707:
	s_add_i32 s94, s94, 1
	s_mul_i32 s4, s94, s33
	s_mul_hi_u32 s5, s94, s70
	s_add_i32 s5, s5, s4
	s_mul_i32 s4, s94, s70
	v_readlane_b32 s6, v255, 29
	s_add_u32 s4, s4, s2
	v_readlane_b32 s7, v255, 30
	s_addc_u32 s5, s5, s71
	s_waitcnt lgkmcnt(0)
	v_mov_b64_e32 v[4:5], s[6:7]
	v_cmp_ge_i64_e32 vcc, s[4:5], v[4:5]
	v_cmp_lt_i64_e64 s[40:41], s[4:5], v[4:5]
	s_cbranch_vccnz .LBB0_709
	s_ashr_i32 s5, s4, 31
	s_lshr_b32 s5, s5, 29
	s_add_i32 s5, s4, s5
	s_ashr_i32 s6, s5, 3
	s_and_b32 s5, s5, -8
	s_sub_i32 s4, s4, s5
	s_lshr_b32 s5, s4, 31
	v_readlane_b32 s7, v255, 26
	s_or_b32 s5, s7, s5
	s_mul_i32 s4, s5, s4
	s_add_i32 s4, s4, s6
	s_ashr_i32 s5, s4, 31
	s_lshr_b32 s5, s5, 28
	s_add_i32 s5, s4, s5
	s_ashr_i32 s6, s5, 4
	s_lshl_b32 s6, s6, 2
	s_sub_i32 s7, s30, s6
	s_min_i32 s7, s7, 4
	s_abs_i32 s20, s7
	v_cvt_f32_u32_e32 v4, s20
	s_sub_i32 s22, 0, s20
	s_and_b32 s5, s5, -16
	s_sub_i32 s4, s4, s5
	v_rcp_iflag_f32_e32 v4, v4
	s_abs_i32 s5, s4
	s_xor_b32 s21, s4, s7
	s_ashr_i32 s21, s21, 31
	v_mul_f32_e32 v4, 0x4f7ffffe, v4
	v_cvt_u32_f32_e32 v4, v4
	s_nop 0
	v_readfirstlane_b32 s23, v4
	s_mul_i32 s22, s22, s23
	s_mul_hi_u32 s22, s23, s22
	s_add_i32 s23, s23, s22
	s_mul_hi_u32 s22, s5, s23
	s_mul_i32 s23, s22, s20
	s_sub_i32 s5, s5, s23
	s_add_i32 s24, s22, 1
	s_sub_i32 s23, s5, s20
	s_cmp_ge_u32 s5, s20
	s_cselect_b32 s22, s24, s22
	s_cselect_b32 s5, s23, s5
	s_add_i32 s23, s22, 1
	s_cmp_ge_u32 s5, s20
	s_cselect_b32 s5, s23, s22
	s_xor_b32 s5, s5, s21
	s_sub_i32 s43, s5, s21
	s_mul_i32 s5, s43, s7
	s_sub_i32 s4, s4, s5
	s_add_i32 s95, s4, s6
	s_sub_i32 s95, s30, s95
	s_add_i32 s95, s95, -1
